# NA per-wave ticket counter claimed 4 task ids per atomic (chunked dequeue) on top of WG ticket prefetch
# baseline (speedup 1.0000x reference)
; __device__ __forceinline__ void mixer_phase(ParamsCP pp, int layer, LAS unsigned char* lds, int tid) {
;     ...
;     for (;;) {
;         unsigned t = 0;
;         if (lane == 0) t = atomicAdd(ctrn, 1u);
;         t = (unsigned)__builtin_amdgcn_readfirstlane((int)t);
;         if (t >= (unsigned)T_NATOTAL) break;
;         int q = (int)t;
.LBB0_451:
	s_add_u32 s4, s78, s52
	s_addc_u32 s5, s79, s53
	s_add_u32 s86, s4, 0x8008
	s_addc_u32 s87, s5, 0
	v_readlane_b32 s4, v254, 49
	v_and_b32_e32 v110, 63, v206
	s_mul_i32 s30, s4, 0x1d10
	s_add_u32 s76, s78, 0x22780000
	v_cmp_eq_u32_e64 s[6:7], 0, v110
	s_addc_u32 s77, s79, 0
	s_lshl_b64 s[48:49], s[30:31], 2
	v_mov_b32_e32 v250, 3
	s_branch .LBB0_454

; __device__ __forceinline__ void mixer_phase(ParamsCP pp, int layer, LAS unsigned char* lds, int tid) {
;     ...
;         unsigned t = 0;
;         if (lane == 0) t = atomicAdd(ctrn, 1u);
;         t = (unsigned)__builtin_amdgcn_readfirstlane((int)t);
;         if (t >= (unsigned)T_NATOTAL) break;
.LBB0_454:
	v_readfirstlane_b32 s8, v250
	s_add_i32 s8, s8, 1
	s_and_b32 s4, s8, 3
	s_cmp_lg_u32 s4, 0
	s_cbranch_scc1 .Lna_have
	v_mov_b32_e32 v0, 0
	s_and_saveexec_b64 s[4:5], s[6:7]
	s_cbranch_execz .LBB0_458
	s_mov_b64 s[10:11], exec
	v_mbcnt_lo_u32_b32 v0, s10, 0
	v_mbcnt_hi_u32_b32 v0, s11, v0
	v_cmp_eq_u32_e32 vcc, 0, v0
	s_and_saveexec_b64 s[8:9], vcc
	s_cbranch_execz .LBB0_457
	s_bcnt1_i32_b64 s10, s[10:11]
	v_mov_b32_e32 v2, 4
	global_atomic_add v2, v1, v2, s[80:81] offset:512 sc0

; __device__ __forceinline__ float fast_exp2(float x) { return __builtin_amdgcn_exp2f(x); }
; __device__ __forceinline__ void na_task(ParamsCP pp, int layer, int b, int h, int r, int g, int lane_in) {
;     ...
;     const int qrow0 = meta ? b * 16 : RB + b * SEQ + r * 64 + 16 * g;
;     bf16x8 qf[2];
;     { const bf16_t* qp = PROJ + 2 * PBUF + (size_t)(qrow0 + c16) * PP + h * 64 + 8 * quad; qf[0] = *(const bf16x8*)qp; qf[1] = *(const bf16x8*)(qp + 32); }
;     f32x4 acc[4];
; #pragma unroll
;     for (int e0 = 0; e0 < 4; ++e0) acc[e0] = (f32x4){0.f, 0.f, 0.f, 0.f};
;     float lsum = 0.f;
;     const size_t colk = 2 * PBUF + 1024 + h * 64 + 8 * quad;
;     const bf16_t* vbase = VT + (size_t)(V_NA + h * 64 + c16) * M + 4 * quad;
;     const int qc = 16 * g + c16;
;     int cstart = qc - 8; cstart = cstart < 0 ? 0 : (cstart > 48 ? 48 : cstart);
;     int rs = r - 4; rs = rs < 0 ? 0 : (rs > 24 ? 24 : rs);
;     int cw0 = 16 * g - 8; cw0 = cw0 < 0 ? 0 : (cw0 > 32 ? 32 : cw0);
;     int bi0[4], bi1[4]; bool ok0[4], ok1[4];
; #pragma unroll
;     for (int rr = 0; rr < 4; ++rr) { const int kc0 = cw0 + 4 * quad + rr, kc1 = kc0 + 16;
;         int i0 = kc0 - qc + 15; i0 = i0 < 0 ? 0 : (i0 > 30 ? 30 : i0); int i1 = kc1 - qc + 15; i1 = i1 < 0 ? 0 : (i1 > 30 ? 30 : i1);
;         bi0[rr] = i0; bi1[rr] = i1; ok0[rr] = kc0 >= cstart && kc0 < cstart + 16; ok1[rr] = kc1 >= cstart && kc1 < cstart + 16; }
;     bf16x8 ck0[2], ck1[2], nk0[2], nk1[2]; u32x2 cva[4], cvb[4], nva[4], nvb[4]; float cb0[4], cb1[4], nb0[4], nb1[4];
;     ...
;     const int sfirst = meta ? 8 : 0;
;     NA_LOAD(ck0, ck1, cva, cvb, cb0, cb1, sfirst);
; #pragma unroll 1
;     for (int s = sfirst; s < 9; ++s) {
;         const bool win = s < 8;
;         if (s + 1 < 9) NA_LOAD(nk0, nk1, nva, nvb, nb0, nb1, s + 1);
;         asm volatile("" ::: "memory");
;         const f32x4 s0 = st_mma<2>(ck0, qf), s1 = st_mma<2>(ck1, qf);
;         float p0[4], p1[4];
; #pragma unroll
;         for (int rr = 0; rr < 4; ++rr) {
;             if (win) { p0[rr] = ok0[rr] ? fast_exp2((s0[rr] * 0.125f + cb0[rr] - bound) * LOG2E) : 0.f; p1[rr] = ok1[rr] ? fast_exp2((s1[rr] * 0.125f + cb1[rr] - bound) * LOG2E) : 0.f; }
;             else { p0[rr] = fast_exp2((s0[rr] * 0.125f - bound) * LOG2E); p1[rr] = 0.f; }
;             lsum += p0[rr] + p1[rr];
;         }
;         const bf16x8 pf = pack_p(p0, p1);
; #pragma unroll
.Lna_have:
	v_mov_b32_e32 v250, s8
	s_cmpk_gt_u32 s8, 0x80ff
	s_mov_b64 s[4:5], -1
	s_cbranch_scc1 .LBB0_453
	s_cmpk_gt_u32 s8, 0x7fff
	s_cbranch_scc0 .LBB0_461
	s_and_b32 s4, s8, 0xfff0
	v_mov_b32_e32 v0, v110
	s_add_i32 s30, s4, 0xffff8000
	s_lshl_b32 s4, s8, 6
	s_and_b32 s4, s4, 0x3c0
	v_and_b32_e32 v28, 15, v0
	v_ashrrev_i32_e32 v10, 4, v0
	v_or_b32_e32 v0, s4, v28
	v_mul_u32_u24_e32 v0, 0x8100, v0
	v_lshlrev_b32_e32 v0, 1, v0
	v_lshlrev_b32_e32 v26, 2, v10
	v_lshl_add_u64 v[2:3], s[78:79], 0, v[0:1]
	v_ashrrev_i32_e32 v27, 31, v26
	v_lshl_add_u64 v[2:3], v[26:27], 1, v[2:3]
	v_lshl_add_u64 v[4:5], s[30:31], 1, v[2:3]
	s_mov_b32 s5, 0x32980000
	v_add_co_u32_e32 v2, vcc, s5, v4
	s_mov_b32 s5, 0x32a82000
	s_nop 0
	v_addc_co_u32_e32 v3, vcc, 0, v5, vcc
	v_add_co_u32_e32 v6, vcc, s5, v4
	s_mov_b32 s5, 0x32b84000
	s_nop 0
	v_addc_co_u32_e32 v7, vcc, 0, v5, vcc
	v_add_co_u32_e32 v8, vcc, s5, v4
	s_mov_b32 s5, 0x32c86000
	s_nop 0
	v_addc_co_u32_e32 v9, vcc, 0, v5, vcc
	v_add_co_u32_e32 v4, vcc, s5, v4
	v_or_b32_e32 v0, s30, v28
	s_nop 0
	v_addc_co_u32_e32 v5, vcc, 0, v5, vcc
	global_load_dword v20, v1, s[86:87]
	global_load_dwordx2 v[22:23], v[4:5], off
	v_lshlrev_b64 v[4:5], 12, v[0:1]
	global_load_dwordx2 v[2:3], v[2:3], off
	v_lshlrev_b32_e32 v10, 3, v10
	global_load_dwordx2 v[6:7], v[6:7], off
	s_lshl_b32 s4, s4, 1
	global_load_dwordx2 v[18:19], v[8:9], off
	v_lshl_add_u64 v[8:9], s[84:85], 0, v[4:5]
	s_mov_b32 s5, s31
	v_ashrrev_i32_e32 v11, 31, v10
	v_lshl_add_u64 v[8:9], v[8:9], 0, s[4:5]
	v_lshlrev_b64 v[16:17], 1, v[10:11]
	v_lshl_add_u64 v[12:13], v[8:9], 0, v[16:17]
	s_mov_b64 s[10:11], 0x10200800
	s_mov_b32 s9, 0x10200000
	v_lshl_add_u64 v[8:9], v[12:13], 0, s[10:11]
	v_add_co_u32_e32 v12, vcc, s9, v12
	global_load_dwordx4 v[8:11], v[8:9], off offset:64
	s_nop 0
	v_addc_co_u32_e32 v13, vcc, 0, v13, vcc
	global_load_dwordx4 v[12:15], v[12:13], off offset:2048
	v_lshl_add_u64 v[4:5], s[76:77], 0, v[4:5]
	v_lshl_add_u64 v[4:5], v[4:5], 0, s[4:5]
	v_lshl_add_u64 v[4:5], v[4:5], 0, v[16:17]
	global_load_dwordx4 v[30:33], v[4:5], off offset:64
	global_load_dwordx4 v[34:37], v[4:5], off
	s_waitcnt vmcnt(0)
	v_mfma_f32_16x16x32_bf16 v[12:15], v[12:15], v[34:37], 0
	v_mov_b32_e32 v21, v19
	v_mov_b32_e32 v24, v22
	v_mov_b32_e32 v25, v23
	v_mfma_f32_16x16x32_bf16 v[8:11], v[8:11], v[30:33], v[12:15]
	v_mov_b32_e32 v32, v1
	v_mov_b32_e32 v33, v1
	s_nop 5
	v_fma_f32 v0, v8, s42, -v20
	v_mul_f32_e32 v0, 0x3fb8aa3b, v0
	v_exp_f32_e32 v4, v0
	v_fma_f32 v0, v9, s42, -v20
	v_mul_f32_e32 v0, 0x3fb8aa3b, v0
	v_exp_f32_e32 v5, v0
	v_fma_f32 v0, v10, s42, -v20
	v_mul_f32_e32 v0, 0x3fb8aa3b, v0
	v_exp_f32_e32 v9, v0
	v_fma_f32 v0, v11, s42, -v20
	v_mul_f32_e32 v0, 0x3fb8aa3b, v0
	v_exp_f32_e32 v8, v0
	v_cvt_pk_bf16_f32 v30, v4, v5
	v_mov_b32_e32 v20, v18
	v_pk_add_f32 v[34:35], v[4:5], 0 op_sel_hi:[1,0]
	v_cvt_pk_bf16_f32 v31, v9, v8
	v_pk_add_f32 v[36:37], v[8:9], 0 op_sel_hi:[1,0]
	v_mov_b32_e32 v8, v6
	v_mov_b32_e32 v9, v7
	v_add_f32_e32 v0, v34, v35
	v_add_f32_e32 v0, v37, v0
	v_mfma_f32_16x16x32_bf16 v[10:13], v[30:33], v[6:9], 0
	v_add_f32_e32 v0, v36, v0
	v_mov_b32_e32 v4, v2
	v_mov_b32_e32 v5, v3
	v_mfma_f32_16x16x32_bf16 v[6:9], v[30:33], v[18:21], 0
	v_and_b32_e32 v19, 64, v239
	v_xor_b32_e32 v18, 16, v239
	v_add_u32_e32 v20, 64, v19
	v_cmp_lt_i32_e32 vcc, v18, v20
	v_mfma_f32_16x16x32_bf16 v[14:17], v[30:33], v[2:5], 0
	s_nop 0
	v_cndmask_b32_e32 v18, v239, v18, vcc
	v_lshlrev_b32_e32 v18, 2, v18
	ds_bpermute_b32 v18, v18, v0
	v_mfma_f32_16x16x32_bf16 v[2:5], v[30:33], v[22:25], 0
	s_waitcnt lgkmcnt(0)
	v_add_f32_e32 v0, v0, v18
	v_xor_b32_e32 v18, 32, v239
	v_cmp_lt_i32_e32 vcc, v18, v20
	s_nop 1
	v_cndmask_b32_e32 v18, v239, v18, vcc
	v_lshlrev_b32_e32 v18, 2, v18
	ds_bpermute_b32 v18, v18, v0
	s_waitcnt lgkmcnt(0)
	v_add_f32_e32 v0, v0, v18
	v_and_or_b32 v18, v26, 60, v19
	v_lshlrev_b32_e32 v18, 2, v18
	ds_bpermute_b32 v19, v18, v0
	s_waitcnt lgkmcnt(0)
; __device__ __forceinline__ unsigned f2bf(float f) { return pk2(f, 0.f) & 0xffffu; }
; __device__ __forceinline__ void na_task(ParamsCP pp, int layer, int b, int h, int r, int g, int lane_in) {
;     ...
;     lsum += __shfl_xor(lsum, 16); lsum += __shfl_xor(lsum, 32);
;     float il[4];
; #pragma unroll
;     for (int rr = 0; rr < 4; ++rr) il[rr] = 1.0f / __shfl(lsum, 4 * quad + rr);
;     bf16_t* yb = (bf16_t*)(pp->ws + WS_BIG + BIG_PROJ) + 2 * PBUF + (size_t)(qrow0 + 4 * quad) * PP + h * 64 + c16;
; #pragma unroll
;     for (int e0 = 0; e0 < 4; ++e0)
; #pragma unroll
;         for (int rr = 0; rr < 4; ++rr) yb[(size_t)rr * PP + e0 * 16] = (bf16_t)f2bf(acc[e0][rr] * il[rr]);
	v_div_scale_f32 v20, s[10:11], v19, v19, 1.0
	v_rcp_f32_e32 v21, v20
	s_nop 0
	v_fma_f32 v22, -v20, v21, 1.0
	v_fmac_f32_e32 v21, v22, v21
	v_div_scale_f32 v22, vcc, 1.0, v19, 1.0
	v_mul_f32_e32 v23, v22, v21
	v_fma_f32 v24, -v20, v23, v22
	v_fmac_f32_e32 v23, v24, v21
	v_fma_f32 v20, -v20, v23, v22
	v_div_fmas_f32 v20, v20, v21, v23
	v_div_fixup_f32 v22, v20, v19, 1.0
	ds_bpermute_b32 v19, v18, v0 offset:4
	s_waitcnt lgkmcnt(0)
	v_div_scale_f32 v20, s[10:11], v19, v19, 1.0
	v_rcp_f32_e32 v21, v20
	s_nop 0
	v_fma_f32 v23, -v20, v21, 1.0
	v_fmac_f32_e32 v21, v23, v21
	v_div_scale_f32 v23, vcc, 1.0, v19, 1.0
	v_mul_f32_e32 v24, v23, v21
	v_fma_f32 v25, -v20, v24, v23
	v_fmac_f32_e32 v24, v25, v21
	v_fma_f32 v20, -v20, v24, v23
	v_div_fmas_f32 v20, v20, v21, v24
	v_div_fixup_f32 v23, v20, v19, 1.0
	ds_bpermute_b32 v19, v18, v0 offset:8
	ds_bpermute_b32 v0, v18, v0 offset:12
	s_waitcnt lgkmcnt(1)
	v_div_scale_f32 v20, s[10:11], v19, v19, 1.0
	v_rcp_f32_e32 v21, v20
	s_waitcnt lgkmcnt(0)
	v_div_scale_f32 v18, s[10:11], v0, v0, 1.0
	v_fma_f32 v24, -v20, v21, 1.0
	v_fmac_f32_e32 v21, v24, v21
	v_div_scale_f32 v24, vcc, 1.0, v19, 1.0
	v_mul_f32_e32 v25, v24, v21
	v_fma_f32 v27, -v20, v25, v24
	v_fmac_f32_e32 v25, v27, v21
	v_fma_f32 v20, -v20, v25, v24
	v_div_fmas_f32 v20, v20, v21, v25
	v_div_fixup_f32 v24, v20, v19, 1.0
	v_rcp_f32_e32 v19, v18
	s_nop 0
	v_fma_f32 v20, -v18, v19, 1.0
	v_fmac_f32_e32 v19, v20, v19
	v_div_scale_f32 v20, vcc, 1.0, v0, 1.0
	v_mul_f32_e32 v21, v20, v19
	v_fma_f32 v25, -v18, v21, v20
	v_fmac_f32_e32 v21, v25, v19
	v_fma_f32 v18, -v18, v21, v20
	v_div_fmas_f32 v18, v18, v19, v21
	v_div_fixup_f32 v25, v18, v0, 1.0
	v_add_u32_e32 v18, s30, v26
	v_ashrrev_i32_e32 v19, 31, v18
	v_lshlrev_b64 v[18:19], 12, v[18:19]
	v_lshl_add_u64 v[18:19], s[76:77], 0, v[18:19]
	v_lshl_add_u64 v[18:19], v[18:19], 0, s[4:5]
	v_lshlrev_b32_e32 v0, 1, v28
	v_lshl_add_u64 v[18:19], v[18:19], 0, v[0:1]
	v_mul_f32_e32 v0, v14, v22
	s_movk_i32 s4, 0x1000
	v_cvt_pk_bf16_f32 v0, v0, s0
	v_add_co_u32_e32 v14, vcc, s4, v18
	global_store_short v[18:19], v0, off
	v_mul_f32_e32 v0, v15, v23
	v_addc_co_u32_e32 v15, vcc, 0, v19, vcc
	s_movk_i32 s4, 0x2000
	v_add_co_u32_e32 v20, vcc, s4, v18
	v_cvt_pk_bf16_f32 v0, v0, s0
	s_nop 0
	v_addc_co_u32_e32 v21, vcc, 0, v19, vcc
	global_store_short v[20:21], v0, off offset:-4096
	v_mul_f32_e32 v0, v16, v24
	v_cvt_pk_bf16_f32 v0, v0, s0
	s_movk_i32 s4, 0x3000
	global_store_short v[20:21], v0, off
	v_mul_f32_e32 v0, v17, v25
	v_add_co_u32_e32 v16, vcc, s4, v18
	v_cvt_pk_bf16_f32 v0, v0, s0
	s_nop 0
	v_addc_co_u32_e32 v17, vcc, 0, v19, vcc
	global_store_short v[16:17], v0, off
	v_mul_f32_e32 v0, v10, v22
	v_cvt_pk_bf16_f32 v0, v0, s0
	global_store_short v[18:19], v0, off offset:32
	v_mul_f32_e32 v0, v11, v23
	v_cvt_pk_bf16_f32 v0, v0, s0
	global_store_short v[14:15], v0, off offset:32
	v_mul_f32_e32 v0, v12, v24
	v_cvt_pk_bf16_f32 v0, v0, s0
	global_store_short v[20:21], v0, off offset:32
	v_mul_f32_e32 v0, v13, v25
	v_cvt_pk_bf16_f32 v0, v0, s0
	global_store_short v[16:17], v0, off offset:32
	v_mul_f32_e32 v0, v6, v22
	v_cvt_pk_bf16_f32 v0, v0, s0
	global_store_short v[18:19], v0, off offset:64
	v_mul_f32_e32 v0, v7, v23
	v_cvt_pk_bf16_f32 v0, v0, s0
	global_store_short v[14:15], v0, off offset:64
	v_mul_f32_e32 v0, v8, v24
	v_cvt_pk_bf16_f32 v0, v0, s0
	global_store_short v[20:21], v0, off offset:64
	v_mul_f32_e32 v0, v9, v25
	v_cvt_pk_bf16_f32 v0, v0, s0
	global_store_short v[16:17], v0, off offset:64
	v_mul_f32_e32 v0, v2, v22
	v_cvt_pk_bf16_f32 v0, v0, s0
	global_store_short v[18:19], v0, off offset:96
	v_mul_f32_e32 v0, v3, v23
	v_cvt_pk_bf16_f32 v0, v0, s0
	global_store_short v[14:15], v0, off offset:96
	v_mul_f32_e32 v0, v4, v24
	v_cvt_pk_bf16_f32 v0, v0, s0
	global_store_short v[20:21], v0, off offset:96
	v_mul_f32_e32 v0, v5, v25
	s_mov_b64 s[4:5], 0
